# prologue bf16 weight/partial stores made write-through (sc0 sc1); retention epilogue deferred
# speedup vs baseline: 1.0018x; 1.0018x over previous
.LBB0_16:
	s_or_b64 exec, exec, s[6:7]
	s_waitcnt lgkmcnt(4)
	v_pk_add_f32 v[4:5], v[16:17], v[18:19]
	v_pk_add_f32 v[16:17], v[24:25], v[30:31]
	s_waitcnt lgkmcnt(0)
	v_pk_add_f32 v[24:25], v[14:15], v[36:37]
	v_add_u32_e32 v14, v8, v12
	v_ashrrev_i32_e32 v15, 31, v14
	s_cmpk_lt_u32 s56, 0x9000
	v_pk_add_f32 v[2:3], v[20:21], v[26:27]
	v_lshl_add_u64 v[14:15], v[14:15], 2, s[48:49]
	s_cselect_b32 s6, s19, 0x1d000
	global_store_dwordx4 v[14:15], v[2:5], off sc0 sc1
	v_pk_add_f32 v[18:19], v[34:35], v[38:39]
	v_pk_add_f32 v[22:23], v[22:23], v[28:29]
	v_mov_b32_e32 v2, s6
	v_cndmask_b32_e32 v2, v2, v44, vcc
	v_add_u32_e32 v2, v2, v12
	v_ashrrev_i32_e32 v3, 31, v2
	v_lshl_add_u64 v[2:3], v[2:3], 2, s[48:49]
	s_cselect_b32 s6, 0x1b000, s20
	global_store_dwordx4 v[2:3], v[16:19], off sc0 sc1
	v_mov_b32_e32 v2, s6
	v_cndmask_b32_e32 v2, v2, v45, vcc
	v_add_u32_e32 v2, v2, v12
	v_ashrrev_i32_e32 v3, 31, v2
	v_lshl_add_u64 v[2:3], v[2:3], 2, s[48:49]
	global_store_dwordx4 v[2:3], v[22:25], off sc0 sc1

.LBB0_25:
	global_load_dwordx4 v[2:5], v[20:21], off nt
	v_lshl_add_u64 v[34:35], v[20:21], 0, s[6:7]
	v_add_u32_e32 v36, s46, v8
	global_load_dwordx4 v[30:33], v[34:35], off nt
	v_lshl_add_u64 v[38:39], v[34:35], 0, s[6:7]
	ds_read2_b32 v[62:63], v36 offset1:8
	v_add_u32_e32 v40, 0x2000, v36
	v_add_u32_e32 v41, 0x4000, v36
	v_add_u32_e32 v48, 0x6000, v36
	ds_read2_b32 v[64:65], v36 offset0:16 offset1:24
	ds_read2_b32 v[66:67], v36 offset0:32 offset1:40
	ds_read2_b32 v[68:69], v36 offset0:48 offset1:56
	global_load_dwordx4 v[34:37], v[38:39], off nt
	v_lshl_add_u64 v[46:47], v[38:39], 0, s[6:7]
	ds_read2_b32 v[70:71], v40 offset1:8
	ds_read2_b32 v[72:73], v41 offset1:8
	ds_read2_b32 v[74:75], v48 offset1:8
	ds_read2_b32 v[76:77], v40 offset0:16 offset1:24
	ds_read2_b32 v[78:79], v41 offset0:16 offset1:24
	ds_read2_b32 v[80:81], v48 offset0:16 offset1:24
	ds_read2_b32 v[82:83], v40 offset0:32 offset1:40
	ds_read2_b32 v[84:85], v41 offset0:32 offset1:40
	ds_read2_b32 v[86:87], v48 offset0:32 offset1:40
	ds_read2_b32 v[88:89], v40 offset0:48 offset1:56
	ds_read2_b32 v[90:91], v41 offset0:48 offset1:56
	ds_read2_b32 v[92:93], v48 offset0:48 offset1:56
	global_load_dwordx4 v[38:41], v[46:47], off nt
	v_lshl_add_u64 v[50:51], v[46:47], 0, s[6:7]
	global_load_dwordx4 v[46:49], v[50:51], off nt
	v_lshl_add_u64 v[54:55], v[50:51], 0, s[6:7]
	global_load_dwordx4 v[50:53], v[54:55], off nt
	v_lshl_add_u64 v[58:59], v[54:55], 0, s[6:7]
	global_load_dwordx4 v[54:57], v[58:59], off nt
	v_lshl_add_u64 v[58:59], v[58:59], 0, s[6:7]
	global_load_dwordx4 v[58:61], v[58:59], off nt
	s_waitcnt lgkmcnt(14)
	v_mov_b32_e32 v94, v63
	s_waitcnt lgkmcnt(11)
	v_mov_b32_e32 v102, v71
	s_waitcnt lgkmcnt(10)
	v_mov_b32_e32 v104, v73
	s_waitcnt lgkmcnt(9)
	v_mov_b32_e32 v106, v75
	v_mov_b32_e32 v96, v65
	s_waitcnt lgkmcnt(8)
	v_mov_b32_e32 v108, v77
	s_waitcnt lgkmcnt(7)
	v_mov_b32_e32 v110, v79
	s_waitcnt lgkmcnt(6)
	v_mov_b32_e32 v112, v81
	v_mov_b32_e32 v98, v67
	s_waitcnt lgkmcnt(5)
	v_mov_b32_e32 v114, v83
	s_waitcnt lgkmcnt(4)
	v_mov_b32_e32 v116, v85
	s_waitcnt lgkmcnt(3)
	v_mov_b32_e32 v118, v87
	s_addk_i32 s46, 0x100
	v_mov_b32_e32 v100, v69
	s_waitcnt lgkmcnt(2)
	v_mov_b32_e32 v120, v89
	s_waitcnt lgkmcnt(1)
	v_mov_b32_e32 v122, v91
	s_waitcnt lgkmcnt(0)
	v_mov_b32_e32 v124, v93
	s_cmpk_eq_i32 s46, 0x400
	v_lshl_add_u64 v[20:21], v[20:21], 0, s[44:45]
	s_waitcnt vmcnt(7)
	v_pk_fma_f32 v[18:19], v[4:5], v[62:63], v[18:19] op_sel_hi:[1,0,1]
	v_pk_fma_f32 v[26:27], v[2:3], v[62:63], v[26:27] op_sel_hi:[1,0,1]
	v_pk_fma_f32 v[16:17], v[4:5], v[70:71], v[16:17] op_sel_hi:[1,0,1]
	v_pk_fma_f32 v[28:29], v[2:3], v[70:71], v[28:29] op_sel_hi:[1,0,1]
	v_pk_fma_f32 v[14:15], v[4:5], v[72:73], v[14:15] op_sel_hi:[1,0,1]
	v_pk_fma_f32 v[24:25], v[2:3], v[72:73], v[24:25] op_sel_hi:[1,0,1]
	v_pk_fma_f32 v[4:5], v[4:5], v[74:75], v[12:13] op_sel_hi:[1,0,1]
	v_pk_fma_f32 v[2:3], v[2:3], v[74:75], v[22:23] op_sel_hi:[1,0,1]
	s_waitcnt vmcnt(6)
	v_pk_fma_f32 v[12:13], v[32:33], v[94:95], v[18:19] op_sel_hi:[1,0,1]
	v_pk_fma_f32 v[18:19], v[30:31], v[94:95], v[26:27] op_sel_hi:[1,0,1]
	v_pk_fma_f32 v[16:17], v[32:33], v[102:103], v[16:17] op_sel_hi:[1,0,1]
	v_pk_fma_f32 v[22:23], v[30:31], v[102:103], v[28:29] op_sel_hi:[1,0,1]
	v_pk_fma_f32 v[14:15], v[32:33], v[104:105], v[14:15] op_sel_hi:[1,0,1]
	v_pk_fma_f32 v[24:25], v[30:31], v[104:105], v[24:25] op_sel_hi:[1,0,1]
	v_pk_fma_f32 v[4:5], v[32:33], v[106:107], v[4:5] op_sel_hi:[1,0,1]
	v_pk_fma_f32 v[2:3], v[30:31], v[106:107], v[2:3] op_sel_hi:[1,0,1]
	s_waitcnt vmcnt(5)
	v_pk_fma_f32 v[12:13], v[36:37], v[64:65], v[12:13] op_sel_hi:[1,0,1]
	v_pk_fma_f32 v[18:19], v[34:35], v[64:65], v[18:19] op_sel_hi:[1,0,1]
	v_pk_fma_f32 v[16:17], v[36:37], v[76:77], v[16:17] op_sel_hi:[1,0,1]
	v_pk_fma_f32 v[22:23], v[34:35], v[76:77], v[22:23] op_sel_hi:[1,0,1]
	v_pk_fma_f32 v[14:15], v[36:37], v[78:79], v[14:15] op_sel_hi:[1,0,1]
	v_pk_fma_f32 v[24:25], v[34:35], v[78:79], v[24:25] op_sel_hi:[1,0,1]
	v_pk_fma_f32 v[4:5], v[36:37], v[80:81], v[4:5] op_sel_hi:[1,0,1]
	v_pk_fma_f32 v[2:3], v[34:35], v[80:81], v[2:3] op_sel_hi:[1,0,1]
	s_waitcnt vmcnt(4)
	v_pk_fma_f32 v[12:13], v[40:41], v[96:97], v[12:13] op_sel_hi:[1,0,1]
	v_pk_fma_f32 v[18:19], v[38:39], v[96:97], v[18:19] op_sel_hi:[1,0,1]
	v_pk_fma_f32 v[16:17], v[40:41], v[108:109], v[16:17] op_sel_hi:[1,0,1]
	v_pk_fma_f32 v[22:23], v[38:39], v[108:109], v[22:23] op_sel_hi:[1,0,1]
	v_pk_fma_f32 v[14:15], v[40:41], v[110:111], v[14:15] op_sel_hi:[1,0,1]
	v_pk_fma_f32 v[24:25], v[38:39], v[110:111], v[24:25] op_sel_hi:[1,0,1]
	v_pk_fma_f32 v[4:5], v[40:41], v[112:113], v[4:5] op_sel_hi:[1,0,1]
	v_pk_fma_f32 v[2:3], v[38:39], v[112:113], v[2:3] op_sel_hi:[1,0,1]
	s_waitcnt vmcnt(3)
	v_pk_fma_f32 v[12:13], v[48:49], v[66:67], v[12:13] op_sel_hi:[1,0,1]
	v_pk_fma_f32 v[18:19], v[46:47], v[66:67], v[18:19] op_sel_hi:[1,0,1]
	v_pk_fma_f32 v[16:17], v[48:49], v[82:83], v[16:17] op_sel_hi:[1,0,1]
	v_pk_fma_f32 v[22:23], v[46:47], v[82:83], v[22:23] op_sel_hi:[1,0,1]
	v_pk_fma_f32 v[14:15], v[48:49], v[84:85], v[14:15] op_sel_hi:[1,0,1]
	v_pk_fma_f32 v[24:25], v[46:47], v[84:85], v[24:25] op_sel_hi:[1,0,1]
	v_pk_fma_f32 v[4:5], v[48:49], v[86:87], v[4:5] op_sel_hi:[1,0,1]
	v_pk_fma_f32 v[2:3], v[46:47], v[86:87], v[2:3] op_sel_hi:[1,0,1]
	s_waitcnt vmcnt(2)
	v_pk_fma_f32 v[12:13], v[52:53], v[98:99], v[12:13] op_sel_hi:[1,0,1]
	v_pk_fma_f32 v[18:19], v[50:51], v[98:99], v[18:19] op_sel_hi:[1,0,1]
	v_pk_fma_f32 v[16:17], v[52:53], v[114:115], v[16:17] op_sel_hi:[1,0,1]
	v_pk_fma_f32 v[22:23], v[50:51], v[114:115], v[22:23] op_sel_hi:[1,0,1]
	v_pk_fma_f32 v[14:15], v[52:53], v[116:117], v[14:15] op_sel_hi:[1,0,1]
	v_pk_fma_f32 v[24:25], v[50:51], v[116:117], v[24:25] op_sel_hi:[1,0,1]
	v_pk_fma_f32 v[4:5], v[52:53], v[118:119], v[4:5] op_sel_hi:[1,0,1]
	v_pk_fma_f32 v[2:3], v[50:51], v[118:119], v[2:3] op_sel_hi:[1,0,1]
	s_waitcnt vmcnt(1)
	v_pk_fma_f32 v[12:13], v[56:57], v[68:69], v[12:13] op_sel_hi:[1,0,1]
	v_pk_fma_f32 v[26:27], v[54:55], v[68:69], v[18:19] op_sel_hi:[1,0,1]
	v_pk_fma_f32 v[16:17], v[56:57], v[88:89], v[16:17] op_sel_hi:[1,0,1]
	v_pk_fma_f32 v[22:23], v[54:55], v[88:89], v[22:23] op_sel_hi:[1,0,1]
	v_pk_fma_f32 v[14:15], v[56:57], v[90:91], v[14:15] op_sel_hi:[1,0,1]
	v_pk_fma_f32 v[24:25], v[54:55], v[90:91], v[24:25] op_sel_hi:[1,0,1]
	v_pk_fma_f32 v[4:5], v[56:57], v[92:93], v[4:5] op_sel_hi:[1,0,1]
	v_pk_fma_f32 v[2:3], v[54:55], v[92:93], v[2:3] op_sel_hi:[1,0,1]
	s_waitcnt vmcnt(0)
	v_pk_fma_f32 v[18:19], v[60:61], v[100:101], v[12:13] op_sel_hi:[1,0,1]
	v_pk_fma_f32 v[26:27], v[58:59], v[100:101], v[26:27] op_sel_hi:[1,0,1]
	v_pk_fma_f32 v[16:17], v[60:61], v[120:121], v[16:17] op_sel_hi:[1,0,1]
	v_pk_fma_f32 v[28:29], v[58:59], v[120:121], v[22:23] op_sel_hi:[1,0,1]
	v_pk_fma_f32 v[14:15], v[60:61], v[122:123], v[14:15] op_sel_hi:[1,0,1]
	v_pk_fma_f32 v[24:25], v[58:59], v[122:123], v[24:25] op_sel_hi:[1,0,1]
	v_pk_fma_f32 v[12:13], v[60:61], v[124:125], v[4:5] op_sel_hi:[1,0,1]
	v_pk_fma_f32 v[22:23], v[58:59], v[124:125], v[2:3] op_sel_hi:[1,0,1]
	s_cbranch_scc0 .LBB0_25
	v_and_b32_e32 v2, 64, v43
	v_add_u32_e32 v5, 64, v2
	v_xor_b32_e32 v2, 8, v43
	v_cmp_lt_i32_e32 vcc, v2, v5
	v_xor_b32_e32 v3, 16, v43
	v_xor_b32_e32 v20, 32, v43
	v_cndmask_b32_e32 v2, v43, v2, vcc
	v_cmp_lt_i32_e32 vcc, v3, v5
	v_lshlrev_b32_e32 v8, 2, v2
	ds_bpermute_b32 v2, v8, v26
	v_cndmask_b32_e32 v3, v43, v3, vcc
	v_cmp_lt_i32_e32 vcc, v20, v5
	ds_bpermute_b32 v4, v8, v28
	v_lshlrev_b32_e32 v46, 2, v3
	v_cndmask_b32_e32 v5, v43, v20, vcc
	ds_bpermute_b32 v3, v8, v27
	v_lshlrev_b32_e32 v47, 2, v5
	ds_bpermute_b32 v5, v8, v29
	ds_bpermute_b32 v30, v8, v24
	ds_bpermute_b32 v31, v8, v25
	s_waitcnt lgkmcnt(3)
	v_pk_add_f32 v[2:3], v[26:27], v[2:3]
	ds_bpermute_b32 v20, v46, v2
	s_waitcnt lgkmcnt(3)
	v_pk_add_f32 v[4:5], v[28:29], v[4:5]
	ds_bpermute_b32 v21, v46, v3
	ds_bpermute_b32 v26, v46, v4
	ds_bpermute_b32 v27, v46, v5
	ds_bpermute_b32 v34, v8, v22
	ds_bpermute_b32 v35, v8, v23
	s_waitcnt lgkmcnt(4)
	v_pk_add_f32 v[2:3], v[2:3], v[20:21]
	ds_bpermute_b32 v36, v8, v14
	s_waitcnt lgkmcnt(3)
	v_pk_add_f32 v[20:21], v[4:5], v[26:27]
	v_pk_add_f32 v[4:5], v[24:25], v[30:31]
	ds_bpermute_b32 v24, v46, v4
	ds_bpermute_b32 v25, v46, v5
	s_waitcnt lgkmcnt(3)
	v_pk_add_f32 v[22:23], v[22:23], v[34:35]
	ds_bpermute_b32 v34, v8, v16
	ds_bpermute_b32 v35, v8, v17
	ds_bpermute_b32 v38, v8, v12
	s_waitcnt lgkmcnt(3)
	v_pk_add_f32 v[24:25], v[4:5], v[24:25]
	ds_bpermute_b32 v4, v8, v18
	ds_bpermute_b32 v5, v8, v19
	ds_bpermute_b32 v37, v8, v15
	s_waitcnt lgkmcnt(4)
	v_pk_add_f32 v[16:17], v[16:17], v[34:35]
	ds_bpermute_b32 v39, v8, v13
	ds_bpermute_b32 v34, v46, v16
	ds_bpermute_b32 v35, v46, v17
	s_waitcnt lgkmcnt(4)
	v_pk_add_f32 v[4:5], v[18:19], v[4:5]
	s_waitcnt lgkmcnt(3)
	v_pk_add_f32 v[14:15], v[14:15], v[36:37]
	s_waitcnt lgkmcnt(2)
	v_pk_add_f32 v[12:13], v[12:13], v[38:39]
	ds_bpermute_b32 v28, v46, v22
	ds_bpermute_b32 v29, v46, v23
	ds_bpermute_b32 v18, v46, v4
	ds_bpermute_b32 v19, v46, v5
	s_waitcnt lgkmcnt(4)
	v_pk_add_f32 v[16:17], v[16:17], v[34:35]
	ds_bpermute_b32 v34, v46, v14
	ds_bpermute_b32 v35, v46, v15
	ds_bpermute_b32 v36, v46, v12
	ds_bpermute_b32 v37, v46, v13
	s_waitcnt lgkmcnt(6)
	v_pk_add_f32 v[22:23], v[22:23], v[28:29]
	s_waitcnt lgkmcnt(4)
	v_pk_add_f32 v[4:5], v[4:5], v[18:19]
	s_waitcnt lgkmcnt(2)
	v_pk_add_f32 v[34:35], v[14:15], v[34:35]
	ds_bpermute_b32 v32, v47, v2
	s_waitcnt lgkmcnt(1)
	v_pk_add_f32 v[14:15], v[12:13], v[36:37]
	ds_bpermute_b32 v33, v47, v3
	ds_bpermute_b32 v26, v47, v20
	ds_bpermute_b32 v27, v47, v21
	ds_bpermute_b32 v30, v47, v24
	ds_bpermute_b32 v31, v47, v25
	ds_bpermute_b32 v28, v47, v22
	ds_bpermute_b32 v29, v47, v23
	ds_bpermute_b32 v40, v47, v4
	ds_bpermute_b32 v41, v47, v5
	ds_bpermute_b32 v18, v47, v16
	ds_bpermute_b32 v19, v47, v17
	ds_bpermute_b32 v38, v47, v34
	ds_bpermute_b32 v39, v47, v35
	ds_bpermute_b32 v36, v47, v14
	ds_bpermute_b32 v37, v47, v15
	s_and_saveexec_b64 s[46:47], s[4:5]
	s_cbranch_execz .LBB0_17
	s_mul_hi_i32 s6, s57, 0xa0000
	s_mul_i32 s57, s57, 0xa0000
	s_add_u32 s48, s3, s57
	v_or_b32_e32 v12, s56, v6
	s_waitcnt lgkmcnt(6)
	v_pk_add_f32 v[4:5], v[4:5], v[40:41]
	v_pk_add_f32 v[2:3], v[2:3], v[32:33]
	s_addc_u32 s49, s14, s6
	v_cmp_gt_i32_e32 vcc, s15, v12
	v_cmp_lt_i32_e64 s[6:7], s16, v12
	s_and_saveexec_b64 s[50:51], s[6:7]
	s_xor_b64 s[6:7], exec, s[50:51]
	s_cbranch_execz .LBB0_29
	s_cmpk_lt_u32 s56, 0x9000
	s_cselect_b32 s44, s17, 0x1b000
	v_add_u32_e32 v8, s44, v12
	v_lshl_add_u64 v[32:33], v[8:9], 2, s[48:49]
	s_cselect_b32 s44, s18, 0x1c000
	global_store_dwordx4 v[32:33], v[2:5], off sc0 sc1
.LBB0_29:
	s_or_saveexec_b64 s[6:7], s[6:7]
	v_mov_b32_e32 v8, s44
	s_xor_b64 exec, exec, s[6:7]
	s_cbranch_execz .LBB0_16
	v_ashrrev_i32_e32 v13, 31, v12
	v_lshl_add_u64 v[32:33], v[12:13], 2, s[48:49]
	v_mov_b32_e32 v8, 0x4800
	global_store_dwordx4 v[32:33], v[2:5], off sc0 sc1
	s_branch .LBB0_16

.LBB0_34:
	s_cmp_gt_i32 s54, 0xafff
	s_mov_b64 s[4:5], -1
	s_cbranch_scc0 .LBB0_68
	s_cmp_gt_u32 s54, 0x107ff
	s_cbranch_scc0 .LBB0_65
	s_cmp_gt_u32 s54, 0x137ff
	s_cbranch_scc0 .LBB0_62
	s_cmp_gt_u32 s54, 0x147ff
	s_cbranch_scc0 .LBB0_59
	s_cmp_gt_u32 s54, 0x14a3f
	s_cbranch_scc0 .LBB0_56
	s_cmp_gt_u32 s54, 0x14e3f
	s_cbranch_scc0 .LBB0_53
	s_cmp_gt_u32 s54, 0x1503f
	s_cbranch_scc0 .LBB0_50
	s_cmp_gt_u32 s54, 0x1533f
	s_cbranch_scc0 .LBB0_43
	s_mov_b64 s[4:5], s[70:71]
	s_load_dwordx2 s[4:5], s[4:5], 0xa0
	s_and_b32 s3, s28, 0x7e0
	s_add_i32 s14, s54, 0xacc0
	s_and_b32 s14, s14, 0xffc0
	s_lshl_b32 s15, s3, 2
	s_waitcnt lgkmcnt(0)
	s_add_u32 s4, s4, s15
	v_or_b32_e32 v42, s14, v5
	s_addc_u32 s5, s5, 0
	v_lshl_add_u64 v[40:41], s[4:5], 0, v[2:3]
	v_lshlrev_b32_e32 v42, 13, v42
	v_mov_b32_e32 v43, v3
	v_lshl_add_u64 v[68:69], v[40:41], 0, v[42:43]
	v_add_co_u32_e32 v44, vcc, s34, v68
	v_or_b32_e32 v74, s3, v20
	s_nop 0
	v_addc_co_u32_e32 v45, vcc, 0, v69, vcc
	v_add_co_u32_e32 v48, vcc, s35, v68
	global_load_dwordx4 v[40:43], v[68:69], off nt
	s_nop 0
	global_load_dwordx4 v[44:47], v[44:45], off nt
	v_addc_co_u32_e32 v49, vcc, 0, v69, vcc
	v_add_co_u32_e32 v52, vcc, s36, v68
	s_lshl_b32 s24, s14, 1
	s_nop 0
	v_addc_co_u32_e32 v53, vcc, 0, v69, vcc
	v_add_co_u32_e32 v56, vcc, s37, v68
	global_load_dwordx4 v[48:51], v[48:49], off nt
	s_nop 0
	global_load_dwordx4 v[52:55], v[52:53], off nt
	v_addc_co_u32_e32 v57, vcc, 0, v69, vcc
	v_add_co_u32_e32 v60, vcc, s40, v68
	v_mov_b32_e32 v75, v3
	s_nop 0
	v_addc_co_u32_e32 v61, vcc, 0, v69, vcc
	global_load_dwordx4 v[56:59], v[56:57], off nt
	s_nop 0
	global_load_dwordx4 v[60:63], v[60:61], off nt
	v_add_co_u32_e32 v64, vcc, s41, v68
	v_lshlrev_b32_e32 v74, 12, v74
	s_nop 0
	v_addc_co_u32_e32 v65, vcc, 0, v69, vcc
	global_load_dwordx4 v[64:67], v[64:65], off nt
	v_add_co_u32_e32 v68, vcc, s44, v68
	v_lshl_add_u64 v[76:77], v[6:7], 0, s[24:25]
	s_nop 0
	v_addc_co_u32_e32 v69, vcc, 0, v69, vcc
	global_load_dwordx4 v[68:71], v[68:69], off nt
	v_or_b32_e32 v72, s3, v5
	v_lshl_add_u64 v[74:75], v[76:77], 0, v[74:75]
	v_mov_b32_e32 v73, v3
	v_lshlrev_b32_e32 v72, 12, v72
	v_lshl_add_u64 v[72:73], v[76:77], 0, v[72:73]
	s_mov_b64 s[4:5], 0
	s_waitcnt vmcnt(7)
	ds_write2_b32 v23, v40, v41 offset1:1
	ds_write2_b32 v24, v42, v43 offset1:1
	s_waitcnt vmcnt(6)
	ds_write2_b32 v25, v44, v45 offset1:1
	ds_write2_b32 v26, v46, v47 offset1:1
	s_waitcnt vmcnt(5)
	ds_write2_b32 v27, v48, v49 offset1:1
	ds_write2_b32 v28, v50, v51 offset1:1
	s_waitcnt vmcnt(4)
	ds_write2_b32 v29, v52, v53 offset1:1
	ds_write2_b32 v30, v54, v55 offset1:1
	s_waitcnt vmcnt(3)
	ds_write2_b32 v31, v56, v57 offset1:1
	ds_write2_b32 v32, v58, v59 offset1:1
	s_waitcnt vmcnt(2)
	ds_write2_b32 v33, v60, v61 offset1:1
	ds_write2_b32 v34, v62, v63 offset1:1
	s_waitcnt vmcnt(1)
	ds_write2_b32 v35, v64, v65 offset1:1
	ds_write2_b32 v36, v66, v67 offset1:1
	s_waitcnt vmcnt(0)
	ds_write2_b32 v37, v68, v69 offset1:1
	ds_write2_b32 v38, v70, v71 offset1:1
	s_waitcnt lgkmcnt(0)
	ds_read2_b32 v[44:45], v39 offset0:33 offset1:41
	ds_read2_b32 v[46:47], v39 offset1:8
	ds_read2_b32 v[48:49], v39 offset0:66 offset1:74
	ds_read2_b32 v[50:51], v39 offset0:99 offset1:107
	ds_read2_b32 v[52:53], v39 offset0:132 offset1:140
	ds_read2_b32 v[54:55], v39 offset0:165 offset1:173
	ds_read2_b32 v[56:57], v39 offset0:198 offset1:206
	ds_read2_b32 v[58:59], v39 offset0:231 offset1:239
	ds_read2_b32 v[60:61], v39 offset0:49 offset1:57
	ds_read2_b32 v[62:63], v39 offset0:16 offset1:24
	ds_read2_b32 v[64:65], v39 offset0:82 offset1:90
	ds_read2_b32 v[66:67], v39 offset0:115 offset1:123
	ds_read2_b32 v[68:69], v39 offset0:148 offset1:156
	ds_read2_b32 v[70:71], v39 offset0:181 offset1:189
	ds_read2_b32 v[78:79], v39 offset0:214 offset1:222
	s_waitcnt lgkmcnt(13)
	v_cvt_pk_bf16_f32 v40, v46, v44
	s_waitcnt lgkmcnt(11)
	v_cvt_pk_bf16_f32 v41, v48, v50
	v_cvt_pk_bf16_f32 v44, v47, v45
	v_cvt_pk_bf16_f32 v45, v49, v51
	ds_read2_b32 v[48:49], v39 offset0:247 offset1:255
	s_waitcnt lgkmcnt(10)
	v_cvt_pk_bf16_f32 v46, v53, v55
	s_waitcnt lgkmcnt(8)
	v_cvt_pk_bf16_f32 v47, v57, v59
	global_store_dwordx4 v[74:75], v[44:47], off sc0 sc1
	v_cvt_pk_bf16_f32 v42, v52, v54
	v_cvt_pk_bf16_f32 v43, v56, v58
	v_or_b32_e32 v44, s3, v21
	v_lshlrev_b32_e32 v44, 12, v44
	v_mov_b32_e32 v45, v3
	global_store_dwordx4 v[72:73], v[40:43], off sc0 sc1
	v_lshl_add_u64 v[44:45], v[76:77], 0, v[44:45]
	s_waitcnt lgkmcnt(6)
	v_cvt_pk_bf16_f32 v40, v62, v60
	s_waitcnt lgkmcnt(4)
	v_cvt_pk_bf16_f32 v41, v64, v66
	s_waitcnt lgkmcnt(2)
	v_cvt_pk_bf16_f32 v42, v68, v70
	s_waitcnt lgkmcnt(0)
	v_cvt_pk_bf16_f32 v43, v78, v48
	global_store_dwordx4 v[44:45], v[40:43], off sc0 sc1
	v_or_b32_e32 v44, s3, v22
	v_lshlrev_b32_e32 v44, 12, v44
	v_mov_b32_e32 v45, v3
	v_cvt_pk_bf16_f32 v40, v63, v61
	v_cvt_pk_bf16_f32 v41, v65, v67
	v_cvt_pk_bf16_f32 v42, v69, v71
	v_cvt_pk_bf16_f32 v43, v79, v49
	v_lshl_add_u64 v[44:45], v[76:77], 0, v[44:45]
	global_store_dwordx4 v[44:45], v[40:43], off sc0 sc1
	s_waitcnt lgkmcnt(0)

.LBB0_48:
	s_lshl_b32 s14, s14, 6
	s_and_b32 s15, 0xffff, s15
	s_and_b32 s14, s14, 0xffc0
	s_lshl_b32 s15, s15, 2
	s_waitcnt lgkmcnt(0)
	s_add_u32 s4, s4, s15
	v_or_b32_e32 v42, s14, v5
	s_addc_u32 s5, s5, 0
	v_lshl_add_u64 v[40:41], s[4:5], 0, v[2:3]
	v_mul_u32_u24_e32 v42, 0x3000, v42
	v_mov_b32_e32 v43, v3
	v_lshl_add_u64 v[68:69], v[40:41], 0, v[42:43]
	v_add_co_u32_e32 v44, vcc, s46, v68
	v_add_u32_e32 v72, s3, v5
	s_nop 0
	v_addc_co_u32_e32 v45, vcc, 0, v69, vcc
	v_add_co_u32_e32 v48, vcc, s36, v68
	global_load_dwordx4 v[40:43], v[68:69], off nt
	s_nop 0
	global_load_dwordx4 v[44:47], v[44:45], off nt
	v_addc_co_u32_e32 v49, vcc, 0, v69, vcc
	v_add_co_u32_e32 v52, vcc, s47, v68
	v_mov_b32_e32 v73, v3
	s_nop 0
	v_addc_co_u32_e32 v53, vcc, 0, v69, vcc
	v_add_co_u32_e32 v56, vcc, s41, v68
	global_load_dwordx4 v[48:51], v[48:49], off nt
	s_nop 0
	global_load_dwordx4 v[52:55], v[52:53], off nt
	v_addc_co_u32_e32 v57, vcc, 0, v69, vcc
	v_add_co_u32_e32 v60, vcc, s48, v68
	s_lshl_b32 s24, s14, 1
	s_nop 0
	v_addc_co_u32_e32 v61, vcc, 0, v69, vcc
	global_load_dwordx4 v[56:59], v[56:57], off nt
	s_nop 0
	global_load_dwordx4 v[60:63], v[60:61], off nt
	v_add_co_u32_e32 v64, vcc, s49, v68
	v_lshlrev_b64 v[72:73], 10, v[72:73]
	s_nop 0
	v_addc_co_u32_e32 v65, vcc, 0, v69, vcc
	global_load_dwordx4 v[64:67], v[64:65], off nt
	v_add_co_u32_e32 v68, vcc, s50, v68
	v_lshl_add_u64 v[76:77], v[8:9], 0, s[24:25]
	s_nop 0
	v_addc_co_u32_e32 v69, vcc, 0, v69, vcc
	global_load_dwordx4 v[68:71], v[68:69], off nt
	v_lshl_add_u64 v[72:73], v[76:77], 0, v[72:73]
	v_add_u32_e32 v74, s3, v20
	v_mov_b32_e32 v75, v3
	v_lshlrev_b64 v[74:75], 10, v[74:75]
	v_lshl_add_u64 v[74:75], v[76:77], 0, v[74:75]
	s_waitcnt vmcnt(7)
	ds_write2_b32 v23, v40, v41 offset1:1
	ds_write2_b32 v24, v42, v43 offset1:1
	s_waitcnt vmcnt(5)
	ds_write2_b32 v27, v48, v49 offset1:1
	ds_write2_b32 v28, v50, v51 offset1:1
	s_waitcnt vmcnt(3)
	ds_write2_b32 v31, v56, v57 offset1:1
	ds_write2_b32 v32, v58, v59 offset1:1
	ds_write2_b32 v25, v44, v45 offset1:1
	ds_write2_b32 v26, v46, v47 offset1:1
	ds_write2_b32 v29, v52, v53 offset1:1
	ds_write2_b32 v30, v54, v55 offset1:1
	s_waitcnt vmcnt(2)
	ds_write2_b32 v33, v60, v61 offset1:1
	ds_write2_b32 v34, v62, v63 offset1:1
	s_waitcnt vmcnt(1)
	ds_write2_b32 v35, v64, v65 offset1:1
	ds_write2_b32 v36, v66, v67 offset1:1
	s_waitcnt vmcnt(0)
	ds_write2_b32 v37, v68, v69 offset1:1
	ds_write2_b32 v38, v70, v71 offset1:1
	s_waitcnt lgkmcnt(0)
	ds_read2_b32 v[44:45], v39 offset0:33 offset1:41
	ds_read2_b32 v[46:47], v39 offset1:8
	ds_read2_b32 v[48:49], v39 offset0:66 offset1:74
	ds_read2_b32 v[50:51], v39 offset0:99 offset1:107
	ds_read2_b32 v[52:53], v39 offset0:132 offset1:140
	ds_read2_b32 v[54:55], v39 offset0:165 offset1:173
	ds_read2_b32 v[56:57], v39 offset0:198 offset1:206
	ds_read2_b32 v[58:59], v39 offset0:231 offset1:239
	ds_read2_b32 v[60:61], v39 offset0:49 offset1:57
	ds_read2_b32 v[62:63], v39 offset0:16 offset1:24
	ds_read2_b32 v[64:65], v39 offset0:82 offset1:90
	ds_read2_b32 v[66:67], v39 offset0:115 offset1:123
	ds_read2_b32 v[68:69], v39 offset0:148 offset1:156
	s_waitcnt lgkmcnt(11)
	v_cvt_pk_bf16_f32 v40, v46, v44
	s_waitcnt lgkmcnt(9)
	v_cvt_pk_bf16_f32 v41, v48, v50
	s_waitcnt lgkmcnt(7)
	v_cvt_pk_bf16_f32 v42, v52, v54
	s_waitcnt lgkmcnt(5)
	v_cvt_pk_bf16_f32 v43, v56, v58
	global_store_dwordx4 v[72:73], v[40:43], off sc0 sc1
	v_cvt_pk_bf16_f32 v44, v47, v45
	v_cvt_pk_bf16_f32 v45, v49, v51
	v_cvt_pk_bf16_f32 v46, v53, v55
	ds_read2_b32 v[48:49], v39 offset0:181 offset1:189
	ds_read2_b32 v[50:51], v39 offset0:214 offset1:222
	ds_read2_b32 v[52:53], v39 offset0:247 offset1:255
	v_cvt_pk_bf16_f32 v47, v57, v59
	global_store_dwordx4 v[74:75], v[44:47], off sc0 sc1
	s_waitcnt lgkmcnt(6)
	v_cvt_pk_bf16_f32 v40, v62, v60
	s_waitcnt lgkmcnt(4)
	v_cvt_pk_bf16_f32 v41, v64, v66
	v_add_u32_e32 v44, s3, v21
	v_mov_b32_e32 v45, v3
	v_lshlrev_b64 v[44:45], 10, v[44:45]
	s_waitcnt lgkmcnt(2)
	v_cvt_pk_bf16_f32 v42, v68, v48
	s_waitcnt lgkmcnt(0)
	v_cvt_pk_bf16_f32 v43, v50, v52
	v_lshl_add_u64 v[44:45], v[76:77], 0, v[44:45]
	global_store_dwordx4 v[44:45], v[40:43], off sc0 sc1
	v_add_u32_e32 v44, s3, v22
	v_mov_b32_e32 v45, v3
	v_lshlrev_b64 v[44:45], 10, v[44:45]
	v_cvt_pk_bf16_f32 v40, v63, v61
	v_cvt_pk_bf16_f32 v41, v65, v67
	v_cvt_pk_bf16_f32 v42, v69, v49
	v_cvt_pk_bf16_f32 v43, v51, v53
	v_lshl_add_u64 v[44:45], v[76:77], 0, v[44:45]
	global_store_dwordx4 v[44:45], v[40:43], off sc0 sc1
	s_waitcnt lgkmcnt(0)

.LBB0_50:
	s_andn2_b64 vcc, exec, s[4:5]
	s_cbranch_vccnz .LBB0_52
	s_mov_b64 s[4:5], s[70:71]
	s_load_dwordx2 s[4:5], s[4:5], 0x88
	s_and_b32 s3, s28, 0x1e0
	s_and_b32 s14, s30, 0x3ffc0
	s_lshl_b32 s15, s3, 2
	v_or_b32_e32 v42, s14, v5
	s_waitcnt lgkmcnt(0)
	s_add_u32 s4, s4, s15
	s_addc_u32 s5, s5, 0
	v_lshl_add_u64 v[40:41], s[4:5], 0, v[2:3]
	v_lshlrev_b32_e32 v42, 11, v42
	v_mov_b32_e32 v43, v3
	v_lshl_add_u64 v[68:69], v[40:41], 0, v[42:43]
	v_add_co_u32_e32 v44, vcc, s51, v68
	v_add_co_u32_e64 v60, s[4:5], s46, v68
	s_nop 0
	v_addc_co_u32_e32 v45, vcc, 0, v69, vcc
	v_add_co_u32_e32 v48, vcc, s45, v68
	global_load_dwordx4 v[40:43], v[68:69], off nt
	s_nop 0
	global_load_dwordx4 v[44:47], v[44:45], off nt
	v_addc_co_u32_e32 v49, vcc, 0, v69, vcc
	v_add_co_u32_e32 v52, vcc, s52, v68
	v_addc_co_u32_e64 v61, s[4:5], 0, v69, s[4:5]
	s_nop 0
	v_addc_co_u32_e32 v53, vcc, 0, v69, vcc
	global_load_dwordx4 v[48:51], v[48:49], off nt
	s_nop 0
	global_load_dwordx4 v[52:55], v[52:53], off nt
	v_add_co_u32_e32 v56, vcc, s34, v68
	global_load_dwordx4 v[60:63], v[60:61], off nt
	s_nop 0
	v_addc_co_u32_e32 v57, vcc, 0, v69, vcc
	global_load_dwordx4 v[56:59], v[56:57], off nt
	v_add_co_u32_e32 v64, vcc, s53, v68
	v_or_b32_e32 v72, s3, v5
	s_nop 0
	v_addc_co_u32_e32 v65, vcc, 0, v69, vcc
	global_load_dwordx4 v[64:67], v[64:65], off nt
	v_add_co_u32_e32 v68, vcc, s56, v68
	s_lshl_b32 s24, s14, 1
	s_nop 0
	v_addc_co_u32_e32 v69, vcc, 0, v69, vcc
	global_load_dwordx4 v[68:71], v[68:69], off nt
	v_mov_b32_e32 v73, v3
	v_or_b32_e32 v74, s3, v20
	v_lshlrev_b32_e32 v72, 12, v72
	v_lshl_add_u64 v[76:77], v[10:11], 0, s[24:25]
	v_mov_b32_e32 v75, v3
	v_lshlrev_b32_e32 v74, 12, v74
	v_lshl_add_u64 v[72:73], v[76:77], 0, v[72:73]
	v_lshl_add_u64 v[74:75], v[76:77], 0, v[74:75]
	s_waitcnt vmcnt(7)
	ds_write2_b32 v23, v40, v41 offset1:1
	ds_write2_b32 v24, v42, v43 offset1:1
	s_waitcnt vmcnt(5)
	ds_write2_b32 v27, v48, v49 offset1:1
	ds_write2_b32 v28, v50, v51 offset1:1
	s_waitcnt vmcnt(2)
	ds_write2_b32 v31, v56, v57 offset1:1
	ds_write2_b32 v32, v58, v59 offset1:1
	ds_write2_b32 v35, v60, v61 offset1:1
	ds_write2_b32 v36, v62, v63 offset1:1
	ds_write2_b32 v25, v44, v45 offset1:1
	ds_write2_b32 v26, v46, v47 offset1:1
	ds_write2_b32 v29, v52, v53 offset1:1
	ds_write2_b32 v30, v54, v55 offset1:1
	s_waitcnt vmcnt(1)
	ds_write2_b32 v33, v64, v65 offset1:1
	ds_write2_b32 v34, v66, v67 offset1:1
	s_waitcnt vmcnt(0)
	ds_write2_b32 v37, v68, v69 offset1:1
	ds_write2_b32 v38, v70, v71 offset1:1
	s_waitcnt lgkmcnt(0)
	ds_read2_b32 v[44:45], v39 offset0:33 offset1:41
	ds_read2_b32 v[46:47], v39 offset1:8
	ds_read2_b32 v[48:49], v39 offset0:66 offset1:74
	ds_read2_b32 v[50:51], v39 offset0:99 offset1:107
	ds_read2_b32 v[52:53], v39 offset0:132 offset1:140
	ds_read2_b32 v[54:55], v39 offset0:165 offset1:173
	ds_read2_b32 v[56:57], v39 offset0:198 offset1:206
	ds_read2_b32 v[58:59], v39 offset0:231 offset1:239
	ds_read2_b32 v[60:61], v39 offset0:49 offset1:57
	ds_read2_b32 v[62:63], v39 offset0:16 offset1:24
	ds_read2_b32 v[64:65], v39 offset0:82 offset1:90
	ds_read2_b32 v[66:67], v39 offset0:115 offset1:123
	ds_read2_b32 v[68:69], v39 offset0:148 offset1:156
	ds_read2_b32 v[70:71], v39 offset0:181 offset1:189
	ds_read2_b32 v[78:79], v39 offset0:214 offset1:222
	ds_read2_b32 v[80:81], v39 offset0:247 offset1:255
	s_waitcnt lgkmcnt(14)
	v_cvt_pk_bf16_f32 v40, v46, v44
	s_waitcnt lgkmcnt(12)
	v_cvt_pk_bf16_f32 v41, v48, v50
	s_waitcnt lgkmcnt(10)
	v_cvt_pk_bf16_f32 v42, v52, v54
	s_waitcnt lgkmcnt(8)
	v_cvt_pk_bf16_f32 v43, v56, v58
	v_cvt_pk_bf16_f32 v44, v47, v45
	v_cvt_pk_bf16_f32 v45, v49, v51
	v_cvt_pk_bf16_f32 v46, v53, v55
	v_cvt_pk_bf16_f32 v47, v57, v59
	global_store_dwordx4 v[72:73], v[40:43], off sc0 sc1
	global_store_dwordx4 v[74:75], v[44:47], off sc0 sc1
	s_waitcnt lgkmcnt(6)
	v_cvt_pk_bf16_f32 v40, v62, v60
	v_or_b32_e32 v44, s3, v21
	v_lshlrev_b32_e32 v44, 12, v44
	v_mov_b32_e32 v45, v3
	s_waitcnt lgkmcnt(4)
	v_cvt_pk_bf16_f32 v41, v64, v66
	s_waitcnt lgkmcnt(2)
	v_cvt_pk_bf16_f32 v42, v68, v70
	s_waitcnt lgkmcnt(0)
	v_cvt_pk_bf16_f32 v43, v78, v80
	v_lshl_add_u64 v[44:45], v[76:77], 0, v[44:45]
	global_store_dwordx4 v[44:45], v[40:43], off sc0 sc1
	v_or_b32_e32 v44, s3, v22
	v_lshlrev_b32_e32 v44, 12, v44
	v_mov_b32_e32 v45, v3
	v_cvt_pk_bf16_f32 v40, v63, v61
	v_cvt_pk_bf16_f32 v41, v65, v67
	v_cvt_pk_bf16_f32 v42, v69, v71
	v_cvt_pk_bf16_f32 v43, v79, v81
	v_lshl_add_u64 v[44:45], v[76:77], 0, v[44:45]
	global_store_dwordx4 v[44:45], v[40:43], off sc0 sc1
	s_waitcnt lgkmcnt(0)

.LBB0_53:
	s_andn2_b64 vcc, exec, s[4:5]
	s_cbranch_vccnz .LBB0_55
	s_mov_b64 s[4:5], s[70:71]
	s_load_dwordx2 s[4:5], s[4:5], 0x80
	s_add_i32 s3, s54, 0xb5c0
	s_lshl_b32 s14, s3, 5
	s_and_b32 s14, s14, 0xfe0
	s_lshr_b32 s3, s3, 1
	s_and_b32 s3, s3, 0x7fc0
	s_lshl_b32 s15, s14, 2
	s_waitcnt lgkmcnt(0)
	s_add_u32 s4, s4, s15
	v_or_b32_e32 v42, s3, v5
	s_addc_u32 s5, s5, 0
	v_lshl_add_u64 v[40:41], s[4:5], 0, v[2:3]
	v_lshlrev_b32_e32 v42, 14, v42
	v_mov_b32_e32 v43, v3
	v_lshl_add_u64 v[68:69], v[40:41], 0, v[42:43]
	v_add_co_u32_e32 v44, vcc, s35, v68
	v_or_b32_e32 v72, s14, v5
	s_nop 0
	v_addc_co_u32_e32 v45, vcc, 0, v69, vcc
	v_add_co_u32_e32 v48, vcc, s37, v68
	global_load_dwordx4 v[40:43], v[68:69], off nt
	s_nop 0
	global_load_dwordx4 v[44:47], v[44:45], off nt
	v_addc_co_u32_e32 v49, vcc, 0, v69, vcc
	v_add_co_u32_e32 v52, vcc, s41, v68
	s_lshl_b32 s24, s3, 1
	s_nop 0
	v_addc_co_u32_e32 v53, vcc, 0, v69, vcc
	v_add_co_u32_e32 v56, vcc, s57, v68
	global_load_dwordx4 v[48:51], v[48:49], off nt
	s_nop 0
	global_load_dwordx4 v[52:55], v[52:53], off nt
	v_addc_co_u32_e32 v57, vcc, 0, v69, vcc
	v_add_co_u32_e32 v60, vcc, s60, v68
	v_mov_b32_e32 v73, v3
	s_nop 0
	v_addc_co_u32_e32 v61, vcc, 0, v69, vcc
	global_load_dwordx4 v[56:59], v[56:57], off nt
	s_nop 0
	global_load_dwordx4 v[60:63], v[60:61], off nt
	v_add_co_u32_e32 v64, vcc, s61, v68
	v_lshlrev_b32_e32 v72, 10, v72
	s_nop 0
	v_addc_co_u32_e32 v65, vcc, 0, v69, vcc
	global_load_dwordx4 v[64:67], v[64:65], off nt
	v_add_co_u32_e32 v68, vcc, s62, v68
	v_lshl_add_u64 v[76:77], v[12:13], 0, s[24:25]
	s_nop 0
	v_addc_co_u32_e32 v69, vcc, 0, v69, vcc
	global_load_dwordx4 v[68:71], v[68:69], off nt
	v_lshl_add_u64 v[72:73], v[76:77], 0, v[72:73]
	v_or_b32_e32 v74, s14, v20
	v_mov_b32_e32 v75, v3
	v_lshlrev_b32_e32 v74, 10, v74
	v_lshl_add_u64 v[74:75], v[76:77], 0, v[74:75]
	s_waitcnt vmcnt(7)
	ds_write2_b32 v23, v40, v41 offset1:1
	ds_write2_b32 v24, v42, v43 offset1:1
	s_waitcnt vmcnt(6)
	ds_write2_b32 v25, v44, v45 offset1:1
	ds_write2_b32 v26, v46, v47 offset1:1
	s_waitcnt vmcnt(5)
	ds_write2_b32 v27, v48, v49 offset1:1
	ds_write2_b32 v28, v50, v51 offset1:1
	s_waitcnt vmcnt(4)
	ds_write2_b32 v29, v52, v53 offset1:1
	ds_write2_b32 v30, v54, v55 offset1:1
	s_waitcnt vmcnt(3)
	ds_write2_b32 v31, v56, v57 offset1:1
	ds_write2_b32 v32, v58, v59 offset1:1
	s_waitcnt vmcnt(2)
	ds_write2_b32 v33, v60, v61 offset1:1
	ds_write2_b32 v34, v62, v63 offset1:1
	s_waitcnt vmcnt(1)
	ds_write2_b32 v35, v64, v65 offset1:1
	ds_write2_b32 v36, v66, v67 offset1:1
	s_waitcnt vmcnt(0)
	ds_write2_b32 v37, v68, v69 offset1:1
	ds_write2_b32 v38, v70, v71 offset1:1
	s_waitcnt lgkmcnt(0)
	ds_read2_b32 v[44:45], v39 offset0:33 offset1:41
	ds_read2_b32 v[46:47], v39 offset1:8
	ds_read2_b32 v[48:49], v39 offset0:66 offset1:74
	ds_read2_b32 v[50:51], v39 offset0:99 offset1:107
	ds_read2_b32 v[52:53], v39 offset0:132 offset1:140
	ds_read2_b32 v[54:55], v39 offset0:165 offset1:173
	ds_read2_b32 v[56:57], v39 offset0:198 offset1:206
	ds_read2_b32 v[58:59], v39 offset0:231 offset1:239
	ds_read2_b32 v[60:61], v39 offset0:49 offset1:57
	ds_read2_b32 v[62:63], v39 offset0:16 offset1:24
	ds_read2_b32 v[64:65], v39 offset0:82 offset1:90
	ds_read2_b32 v[66:67], v39 offset0:115 offset1:123
	ds_read2_b32 v[68:69], v39 offset0:148 offset1:156
	s_waitcnt lgkmcnt(11)
	v_cvt_pk_bf16_f32 v40, v46, v44
	s_waitcnt lgkmcnt(9)
	v_cvt_pk_bf16_f32 v41, v48, v50
	s_waitcnt lgkmcnt(7)
	v_cvt_pk_bf16_f32 v42, v52, v54
	s_waitcnt lgkmcnt(5)
	v_cvt_pk_bf16_f32 v43, v56, v58
	global_store_dwordx4 v[72:73], v[40:43], off sc0 sc1
	v_cvt_pk_bf16_f32 v44, v47, v45
	v_cvt_pk_bf16_f32 v45, v49, v51
	v_cvt_pk_bf16_f32 v46, v53, v55
	ds_read2_b32 v[48:49], v39 offset0:181 offset1:189
	ds_read2_b32 v[50:51], v39 offset0:214 offset1:222
	ds_read2_b32 v[52:53], v39 offset0:247 offset1:255
	v_cvt_pk_bf16_f32 v47, v57, v59
	global_store_dwordx4 v[74:75], v[44:47], off sc0 sc1
	s_waitcnt lgkmcnt(6)
	v_cvt_pk_bf16_f32 v40, v62, v60
	s_waitcnt lgkmcnt(4)
	v_cvt_pk_bf16_f32 v41, v64, v66
	v_or_b32_e32 v44, s14, v21
	v_lshlrev_b32_e32 v44, 10, v44
	v_mov_b32_e32 v45, v3
	s_waitcnt lgkmcnt(2)
	v_cvt_pk_bf16_f32 v42, v68, v48
	s_waitcnt lgkmcnt(0)
	v_cvt_pk_bf16_f32 v43, v50, v52
	v_lshl_add_u64 v[44:45], v[76:77], 0, v[44:45]
	global_store_dwordx4 v[44:45], v[40:43], off sc0 sc1
	v_or_b32_e32 v44, s14, v22
	v_lshlrev_b32_e32 v44, 10, v44
	v_mov_b32_e32 v45, v3
	v_cvt_pk_bf16_f32 v40, v63, v61
	v_cvt_pk_bf16_f32 v41, v65, v67
	v_cvt_pk_bf16_f32 v42, v69, v49
	v_cvt_pk_bf16_f32 v43, v51, v53
	v_lshl_add_u64 v[44:45], v[76:77], 0, v[44:45]
	global_store_dwordx4 v[44:45], v[40:43], off sc0 sc1
	s_waitcnt lgkmcnt(0)

.LBB0_56:
	s_andn2_b64 vcc, exec, s[4:5]
	s_cbranch_vccnz .LBB0_58
	s_add_i32 s3, s54, 0xb800
	s_and_b32 s14, s3, 0xffff
	s_mul_i32 s14, s14, 0xe38f
	s_lshr_b32 s14, s14, 20
	s_mov_b64 s[4:5], s[70:71]
	s_mul_i32 s15, s14, 18
	s_sub_i32 s3, s3, s15
	s_load_dwordx2 s[4:5], s[4:5], 0x70
	s_lshl_b32 s15, s3, 5
	s_and_b32 s15, s15, 0xffe0
	s_and_b32 s3, s3, 0xffff
	s_add_i32 s16, s15, 0x60
	s_cmp_lt_u32 s3, 17
	s_cselect_b32 s3, s15, s16
	s_lshl_b32 s15, s15, 2
	s_waitcnt lgkmcnt(0)
	s_add_u32 s4, s4, s15
	v_lshl_or_b32 v42, s14, 6, v5
	s_addc_u32 s5, s5, 0
	v_lshl_add_u64 v[40:41], s[4:5], 0, v[2:3]
	v_mul_u32_u24_e32 v42, 0x900, v42
	v_mov_b32_e32 v43, v3
	v_lshl_add_u64 v[68:69], v[40:41], 0, v[42:43]
	v_add_co_u32_e32 v44, vcc, s51, v68
	v_or_b32_e32 v72, s3, v5
	s_nop 0
	v_addc_co_u32_e32 v45, vcc, 0, v69, vcc
	v_add_co_u32_e32 v48, vcc, s63, v68
	global_load_dwordx4 v[40:43], v[68:69], off nt
	s_nop 0
	global_load_dwordx4 v[44:47], v[44:45], off offset:2048 nt
	v_addc_co_u32_e32 v49, vcc, 0, v69, vcc
	v_add_co_u32_e32 v52, vcc, s64, v68
	s_lshl_b32 s24, s14, 7
	s_nop 0
	v_addc_co_u32_e32 v53, vcc, 0, v69, vcc
	v_add_co_u32_e32 v56, vcc, s65, v68
	global_load_dwordx4 v[48:51], v[48:49], off nt
	s_nop 0
	global_load_dwordx4 v[52:55], v[52:53], off offset:2048 nt
	v_addc_co_u32_e32 v57, vcc, 0, v69, vcc
	v_add_co_u32_e32 v60, vcc, s66, v68
	v_mov_b32_e32 v73, v3
	s_nop 0
	v_addc_co_u32_e32 v61, vcc, 0, v69, vcc
	global_load_dwordx4 v[56:59], v[56:57], off nt
	s_nop 0
	global_load_dwordx4 v[60:63], v[60:61], off offset:2048 nt
	v_add_co_u32_e32 v64, vcc, s67, v68
	v_lshlrev_b32_e32 v72, 12, v72
	s_nop 0
	v_addc_co_u32_e32 v65, vcc, 0, v69, vcc
	global_load_dwordx4 v[64:67], v[64:65], off nt
	v_add_co_u32_e32 v68, vcc, s68, v68
	v_lshl_add_u64 v[76:77], v[14:15], 0, s[24:25]
	s_nop 0
	v_addc_co_u32_e32 v69, vcc, 0, v69, vcc
	global_load_dwordx4 v[68:71], v[68:69], off offset:2048 nt
	v_lshl_add_u64 v[72:73], v[76:77], 0, v[72:73]
	v_or_b32_e32 v74, s3, v20
	v_mov_b32_e32 v75, v3
	v_lshlrev_b32_e32 v74, 12, v74
	v_lshl_add_u64 v[74:75], v[76:77], 0, v[74:75]
	s_waitcnt vmcnt(7)
	ds_write2_b32 v23, v40, v41 offset1:1
	ds_write2_b32 v24, v42, v43 offset1:1
	s_waitcnt vmcnt(6)
	ds_write2_b32 v25, v44, v45 offset1:1
	ds_write2_b32 v26, v46, v47 offset1:1
	s_waitcnt vmcnt(5)
	ds_write2_b32 v27, v48, v49 offset1:1
	ds_write2_b32 v28, v50, v51 offset1:1
	s_waitcnt vmcnt(4)
	ds_write2_b32 v29, v52, v53 offset1:1
	ds_write2_b32 v30, v54, v55 offset1:1
	s_waitcnt vmcnt(3)
	ds_write2_b32 v31, v56, v57 offset1:1
	ds_write2_b32 v32, v58, v59 offset1:1
	s_waitcnt vmcnt(2)
	ds_write2_b32 v33, v60, v61 offset1:1
	ds_write2_b32 v34, v62, v63 offset1:1
	s_waitcnt vmcnt(1)
	ds_write2_b32 v35, v64, v65 offset1:1
	ds_write2_b32 v36, v66, v67 offset1:1
	s_waitcnt vmcnt(0)
	ds_write2_b32 v37, v68, v69 offset1:1
	ds_write2_b32 v38, v70, v71 offset1:1
	s_waitcnt lgkmcnt(0)
	ds_read2_b32 v[44:45], v39 offset0:33 offset1:41
	ds_read2_b32 v[46:47], v39 offset1:8
	ds_read2_b32 v[48:49], v39 offset0:66 offset1:74
	ds_read2_b32 v[50:51], v39 offset0:99 offset1:107
	ds_read2_b32 v[52:53], v39 offset0:132 offset1:140
	ds_read2_b32 v[54:55], v39 offset0:165 offset1:173
	ds_read2_b32 v[56:57], v39 offset0:198 offset1:206
	ds_read2_b32 v[58:59], v39 offset0:231 offset1:239
	ds_read2_b32 v[60:61], v39 offset0:49 offset1:57
	ds_read2_b32 v[62:63], v39 offset0:16 offset1:24
	s_waitcnt lgkmcnt(8)
	v_cvt_pk_bf16_f32 v40, v46, v44
	s_waitcnt lgkmcnt(6)
	v_cvt_pk_bf16_f32 v41, v48, v50
	s_waitcnt lgkmcnt(4)
	v_cvt_pk_bf16_f32 v42, v52, v54
	s_waitcnt lgkmcnt(2)
	v_cvt_pk_bf16_f32 v43, v56, v58
	global_store_dwordx4 v[72:73], v[40:43], off sc0 sc1
	v_cvt_pk_bf16_f32 v44, v47, v45
	v_cvt_pk_bf16_f32 v45, v49, v51
	v_cvt_pk_bf16_f32 v46, v53, v55
	v_cvt_pk_bf16_f32 v47, v57, v59
	ds_read2_b32 v[48:49], v39 offset0:82 offset1:90
	ds_read2_b32 v[50:51], v39 offset0:115 offset1:123
	ds_read2_b32 v[52:53], v39 offset0:148 offset1:156
	ds_read2_b32 v[54:55], v39 offset0:181 offset1:189
	ds_read2_b32 v[56:57], v39 offset0:214 offset1:222
	ds_read2_b32 v[58:59], v39 offset0:247 offset1:255
	global_store_dwordx4 v[74:75], v[44:47], off sc0 sc1
	s_waitcnt lgkmcnt(6)
	v_cvt_pk_bf16_f32 v40, v62, v60
	s_waitcnt lgkmcnt(4)
	v_cvt_pk_bf16_f32 v41, v48, v50
	v_or_b32_e32 v44, s3, v21
	v_lshlrev_b32_e32 v44, 12, v44
	v_mov_b32_e32 v45, v3
	s_waitcnt lgkmcnt(2)
	v_cvt_pk_bf16_f32 v42, v52, v54
	s_waitcnt lgkmcnt(0)
	v_cvt_pk_bf16_f32 v43, v56, v58
	v_lshl_add_u64 v[44:45], v[76:77], 0, v[44:45]
	global_store_dwordx4 v[44:45], v[40:43], off sc0 sc1
	v_or_b32_e32 v44, s3, v22
	v_lshlrev_b32_e32 v44, 12, v44
	v_mov_b32_e32 v45, v3
	v_cvt_pk_bf16_f32 v40, v63, v61
	v_cvt_pk_bf16_f32 v41, v49, v51
	v_cvt_pk_bf16_f32 v42, v53, v55
	v_cvt_pk_bf16_f32 v43, v57, v59
	v_lshl_add_u64 v[44:45], v[76:77], 0, v[44:45]
	global_store_dwordx4 v[44:45], v[40:43], off sc0 sc1
	s_waitcnt lgkmcnt(0)

.LBB0_59:
	s_andn2_b64 vcc, exec, s[4:5]
	s_cbranch_vccnz .LBB0_61
	s_mov_b64 s[4:5], s[70:71]
	s_load_dwordx2 s[4:5], s[4:5], 0x50
	s_add_i32 s3, s54, 0xc800
	s_and_b32 s14, s28, 0x7e0
	s_and_b32 s3, s3, 0xffc0
	s_lshl_b32 s15, s14, 2
	s_waitcnt lgkmcnt(0)
	s_add_u32 s4, s4, s15
	v_or_b32_e32 v42, s3, v5
	s_addc_u32 s5, s5, 0
	v_lshl_add_u64 v[40:41], s[4:5], 0, v[2:3]
	v_lshlrev_b32_e32 v42, 13, v42
	v_mov_b32_e32 v43, v3
	v_lshl_add_u64 v[68:69], v[40:41], 0, v[42:43]
	v_add_co_u32_e32 v44, vcc, s34, v68
	v_or_b32_e32 v74, s14, v20
	s_nop 0
	v_addc_co_u32_e32 v45, vcc, 0, v69, vcc
	v_add_co_u32_e32 v48, vcc, s35, v68
	global_load_dwordx4 v[40:43], v[68:69], off nt
	s_nop 0
	global_load_dwordx4 v[44:47], v[44:45], off nt
	v_addc_co_u32_e32 v49, vcc, 0, v69, vcc
	v_add_co_u32_e32 v52, vcc, s36, v68
	s_lshl_b32 s24, s3, 1
	s_nop 0
	v_addc_co_u32_e32 v53, vcc, 0, v69, vcc
	v_add_co_u32_e32 v56, vcc, s37, v68
	global_load_dwordx4 v[48:51], v[48:49], off nt
	s_nop 0
	global_load_dwordx4 v[52:55], v[52:53], off nt
	v_addc_co_u32_e32 v57, vcc, 0, v69, vcc
	v_add_co_u32_e32 v60, vcc, s40, v68
	v_mov_b32_e32 v75, v3
	s_nop 0
	v_addc_co_u32_e32 v61, vcc, 0, v69, vcc
	global_load_dwordx4 v[56:59], v[56:57], off nt
	s_nop 0
	global_load_dwordx4 v[60:63], v[60:61], off nt
	v_add_co_u32_e32 v64, vcc, s41, v68
	v_lshlrev_b32_e32 v74, 13, v74
	s_nop 0
	v_addc_co_u32_e32 v65, vcc, 0, v69, vcc
	global_load_dwordx4 v[64:67], v[64:65], off nt
	v_add_co_u32_e32 v68, vcc, s44, v68
	v_lshl_add_u64 v[76:77], v[16:17], 0, s[24:25]
	s_nop 0
	v_addc_co_u32_e32 v69, vcc, 0, v69, vcc
	global_load_dwordx4 v[68:71], v[68:69], off nt
	v_or_b32_e32 v72, s14, v5
	v_lshl_add_u64 v[74:75], v[76:77], 0, v[74:75]
	v_mov_b32_e32 v73, v3
	v_lshlrev_b32_e32 v72, 13, v72
	v_lshl_add_u64 v[72:73], v[76:77], 0, v[72:73]
	s_waitcnt vmcnt(7)
	ds_write2_b32 v23, v40, v41 offset1:1
	ds_write2_b32 v24, v42, v43 offset1:1
	s_waitcnt vmcnt(6)
	ds_write2_b32 v25, v44, v45 offset1:1
	ds_write2_b32 v26, v46, v47 offset1:1
	s_waitcnt vmcnt(5)
	ds_write2_b32 v27, v48, v49 offset1:1
	ds_write2_b32 v28, v50, v51 offset1:1
	s_waitcnt vmcnt(4)
	ds_write2_b32 v29, v52, v53 offset1:1
	ds_write2_b32 v30, v54, v55 offset1:1
	s_waitcnt vmcnt(3)
	ds_write2_b32 v31, v56, v57 offset1:1
	ds_write2_b32 v32, v58, v59 offset1:1
	s_waitcnt vmcnt(2)
	ds_write2_b32 v33, v60, v61 offset1:1
	ds_write2_b32 v34, v62, v63 offset1:1
	s_waitcnt vmcnt(1)
	ds_write2_b32 v35, v64, v65 offset1:1
	ds_write2_b32 v36, v66, v67 offset1:1
	s_waitcnt vmcnt(0)
	ds_write2_b32 v37, v68, v69 offset1:1
	ds_write2_b32 v38, v70, v71 offset1:1
	s_waitcnt lgkmcnt(0)
	ds_read2_b32 v[44:45], v39 offset0:33 offset1:41
	ds_read2_b32 v[46:47], v39 offset1:8
	ds_read2_b32 v[48:49], v39 offset0:66 offset1:74
	ds_read2_b32 v[50:51], v39 offset0:99 offset1:107
	ds_read2_b32 v[52:53], v39 offset0:132 offset1:140
	ds_read2_b32 v[54:55], v39 offset0:165 offset1:173
	ds_read2_b32 v[56:57], v39 offset0:198 offset1:206
	ds_read2_b32 v[58:59], v39 offset0:231 offset1:239
	ds_read2_b32 v[60:61], v39 offset0:49 offset1:57
	ds_read2_b32 v[62:63], v39 offset0:16 offset1:24
	ds_read2_b32 v[64:65], v39 offset0:82 offset1:90
	ds_read2_b32 v[66:67], v39 offset0:115 offset1:123
	ds_read2_b32 v[68:69], v39 offset0:148 offset1:156
	ds_read2_b32 v[70:71], v39 offset0:181 offset1:189
	ds_read2_b32 v[78:79], v39 offset0:214 offset1:222
	s_waitcnt lgkmcnt(13)
	v_cvt_pk_bf16_f32 v40, v46, v44
	s_waitcnt lgkmcnt(11)
	v_cvt_pk_bf16_f32 v41, v48, v50
	v_cvt_pk_bf16_f32 v44, v47, v45
	v_cvt_pk_bf16_f32 v45, v49, v51
	ds_read2_b32 v[48:49], v39 offset0:247 offset1:255
	s_waitcnt lgkmcnt(10)
	v_cvt_pk_bf16_f32 v46, v53, v55
	s_waitcnt lgkmcnt(8)
	v_cvt_pk_bf16_f32 v47, v57, v59
	global_store_dwordx4 v[74:75], v[44:47], off sc0 sc1
	v_cvt_pk_bf16_f32 v42, v52, v54
	v_cvt_pk_bf16_f32 v43, v56, v58
	v_or_b32_e32 v44, s14, v21
	v_lshlrev_b32_e32 v44, 13, v44
	v_mov_b32_e32 v45, v3
	global_store_dwordx4 v[72:73], v[40:43], off sc0 sc1
	v_lshl_add_u64 v[44:45], v[76:77], 0, v[44:45]
	s_waitcnt lgkmcnt(6)
	v_cvt_pk_bf16_f32 v40, v62, v60
	s_waitcnt lgkmcnt(4)
	v_cvt_pk_bf16_f32 v41, v64, v66
	s_waitcnt lgkmcnt(2)
	v_cvt_pk_bf16_f32 v42, v68, v70
	s_waitcnt lgkmcnt(0)
	v_cvt_pk_bf16_f32 v43, v78, v48
	global_store_dwordx4 v[44:45], v[40:43], off sc0 sc1
	v_or_b32_e32 v44, s14, v22
	v_lshlrev_b32_e32 v44, 13, v44
	v_mov_b32_e32 v45, v3
	v_cvt_pk_bf16_f32 v40, v63, v61
	v_cvt_pk_bf16_f32 v41, v65, v67
	v_cvt_pk_bf16_f32 v42, v69, v71
	v_cvt_pk_bf16_f32 v43, v79, v49
	v_lshl_add_u64 v[44:45], v[76:77], 0, v[44:45]
	global_store_dwordx4 v[44:45], v[40:43], off sc0 sc1
	s_waitcnt lgkmcnt(0)

.LBB0_62:
	s_andn2_b64 vcc, exec, s[4:5]
	s_cbranch_vccnz .LBB0_64
	s_add_i32 s3, s54, 0xf800
	s_and_b32 s14, s3, 0xffff
	s_mov_b64 s[4:5], s[70:71]
	s_mul_i32 s14, s14, 0xaaab
	s_lshr_b32 s14, s14, 24
	s_load_dwordx2 s[4:5], s[4:5], 0x40
	s_mul_i32 s15, s14, 0x180
	s_sub_i32 s3, s3, s15
	s_lshl_b32 s3, s3, 5
	s_and_b32 s3, s3, 0xffe0
	s_lshl_b32 s15, s3, 2
	s_waitcnt lgkmcnt(0)
	s_add_u32 s4, s4, s15
	v_lshl_or_b32 v42, s14, 6, v5
	s_addc_u32 s5, s5, 0
	v_lshl_add_u64 v[40:41], s[4:5], 0, v[2:3]
	v_mul_u32_u24_e32 v42, 0xc000, v42
	v_mov_b32_e32 v43, v3
	v_lshl_add_u64 v[68:69], v[40:41], 0, v[42:43]
	v_add_co_u32_e32 v44, vcc, s41, v68
	v_or_b32_e32 v72, s3, v5
	s_nop 0
	v_addc_co_u32_e32 v45, vcc, 0, v69, vcc
	v_add_co_u32_e32 v48, vcc, s61, v68
	global_load_dwordx4 v[40:43], v[68:69], off nt
	s_nop 0
	global_load_dwordx4 v[44:47], v[44:45], off nt
	v_addc_co_u32_e32 v49, vcc, 0, v69, vcc
	v_add_co_u32_e32 v52, vcc, s69, v68
	s_lshl_b32 s24, s14, 7
	s_nop 0
	v_addc_co_u32_e32 v53, vcc, 0, v69, vcc
	v_add_co_u32_e32 v56, vcc, s73, v68
	global_load_dwordx4 v[48:51], v[48:49], off nt
	s_nop 0
	global_load_dwordx4 v[52:55], v[52:53], off nt
	v_addc_co_u32_e32 v57, vcc, 0, v69, vcc
	v_add_co_u32_e32 v60, vcc, s74, v68
	v_mov_b32_e32 v73, v3
	s_nop 0
	v_addc_co_u32_e32 v61, vcc, 0, v69, vcc
	global_load_dwordx4 v[56:59], v[56:57], off nt
	s_nop 0
	global_load_dwordx4 v[60:63], v[60:61], off nt
	v_add_co_u32_e32 v64, vcc, s75, v68
	v_lshlrev_b32_e32 v72, 12, v72
	s_nop 0
	v_addc_co_u32_e32 v65, vcc, 0, v69, vcc
	global_load_dwordx4 v[64:67], v[64:65], off nt
	v_add_co_u32_e32 v68, vcc, s76, v68
	v_lshl_add_u64 v[76:77], v[18:19], 0, s[24:25]
	s_nop 0
	v_addc_co_u32_e32 v69, vcc, 0, v69, vcc
	global_load_dwordx4 v[68:71], v[68:69], off nt
	v_lshl_add_u64 v[72:73], v[76:77], 0, v[72:73]
	v_or_b32_e32 v74, s3, v20
	v_mov_b32_e32 v75, v3
	v_lshlrev_b32_e32 v74, 12, v74
	v_lshl_add_u64 v[74:75], v[76:77], 0, v[74:75]
	s_waitcnt vmcnt(7)
	ds_write2_b32 v23, v40, v41 offset1:1
	ds_write2_b32 v24, v42, v43 offset1:1
	s_waitcnt vmcnt(6)
	ds_write2_b32 v25, v44, v45 offset1:1
	ds_write2_b32 v26, v46, v47 offset1:1
	s_waitcnt vmcnt(5)
	ds_write2_b32 v27, v48, v49 offset1:1
	ds_write2_b32 v28, v50, v51 offset1:1
	s_waitcnt vmcnt(4)
	ds_write2_b32 v29, v52, v53 offset1:1
	ds_write2_b32 v30, v54, v55 offset1:1
	s_waitcnt vmcnt(3)
	ds_write2_b32 v31, v56, v57 offset1:1
	ds_write2_b32 v32, v58, v59 offset1:1
	s_waitcnt vmcnt(2)
	ds_write2_b32 v33, v60, v61 offset1:1
	ds_write2_b32 v34, v62, v63 offset1:1
	s_waitcnt vmcnt(1)
	ds_write2_b32 v35, v64, v65 offset1:1
	ds_write2_b32 v36, v66, v67 offset1:1
	s_waitcnt vmcnt(0)
	ds_write2_b32 v37, v68, v69 offset1:1
	ds_write2_b32 v38, v70, v71 offset1:1
	s_waitcnt lgkmcnt(0)
	ds_read2_b32 v[44:45], v39 offset0:33 offset1:41
	ds_read2_b32 v[46:47], v39 offset1:8
	ds_read2_b32 v[48:49], v39 offset0:66 offset1:74
	ds_read2_b32 v[50:51], v39 offset0:99 offset1:107
	ds_read2_b32 v[52:53], v39 offset0:132 offset1:140
	ds_read2_b32 v[54:55], v39 offset0:165 offset1:173
	ds_read2_b32 v[56:57], v39 offset0:198 offset1:206
	ds_read2_b32 v[58:59], v39 offset0:231 offset1:239
	ds_read2_b32 v[60:61], v39 offset0:49 offset1:57
	ds_read2_b32 v[62:63], v39 offset0:16 offset1:24
	ds_read2_b32 v[64:65], v39 offset0:82 offset1:90
	ds_read2_b32 v[66:67], v39 offset0:115 offset1:123
	s_waitcnt lgkmcnt(10)
	v_cvt_pk_bf16_f32 v40, v46, v44
	s_waitcnt lgkmcnt(8)
	v_cvt_pk_bf16_f32 v41, v48, v50
	s_waitcnt lgkmcnt(6)
	v_cvt_pk_bf16_f32 v42, v52, v54
	s_waitcnt lgkmcnt(4)
	v_cvt_pk_bf16_f32 v43, v56, v58
	global_store_dwordx4 v[72:73], v[40:43], off sc0 sc1
	v_cvt_pk_bf16_f32 v44, v47, v45
	v_cvt_pk_bf16_f32 v45, v49, v51
	v_cvt_pk_bf16_f32 v46, v53, v55
	ds_read2_b32 v[48:49], v39 offset0:148 offset1:156
	ds_read2_b32 v[50:51], v39 offset0:181 offset1:189
	ds_read2_b32 v[52:53], v39 offset0:214 offset1:222
	ds_read2_b32 v[54:55], v39 offset0:247 offset1:255
	v_cvt_pk_bf16_f32 v47, v57, v59
	global_store_dwordx4 v[74:75], v[44:47], off sc0 sc1
	s_waitcnt lgkmcnt(6)
	v_cvt_pk_bf16_f32 v40, v62, v60
	s_waitcnt lgkmcnt(4)
	v_cvt_pk_bf16_f32 v41, v64, v66
	v_or_b32_e32 v44, s3, v21
	v_lshlrev_b32_e32 v44, 12, v44
	v_mov_b32_e32 v45, v3
	s_waitcnt lgkmcnt(2)
	v_cvt_pk_bf16_f32 v42, v48, v50
	s_waitcnt lgkmcnt(0)
	v_cvt_pk_bf16_f32 v43, v52, v54
	v_lshl_add_u64 v[44:45], v[76:77], 0, v[44:45]
	global_store_dwordx4 v[44:45], v[40:43], off sc0 sc1
	v_or_b32_e32 v44, s3, v22
	v_lshlrev_b32_e32 v44, 12, v44
	v_mov_b32_e32 v45, v3
	v_cvt_pk_bf16_f32 v40, v63, v61
	v_cvt_pk_bf16_f32 v41, v65, v67
	v_cvt_pk_bf16_f32 v42, v49, v51
	v_cvt_pk_bf16_f32 v43, v53, v55
	v_lshl_add_u64 v[44:45], v[76:77], 0, v[44:45]
	global_store_dwordx4 v[44:45], v[40:43], off sc0 sc1
	s_waitcnt lgkmcnt(0)

.LBB0_65:
	s_andn2_b64 vcc, exec, s[4:5]
	s_cbranch_vccnz .LBB0_67
	s_mov_b64 s[4:5], s[70:71]
	s_add_i32 s3, s54, 0x5000
	s_load_dwordx2 s[4:5], s[4:5], 0x38
	s_and_b32 s14, s3, 0xffff
	s_mul_i32 s14, s14, 0xba2f
	s_lshr_b32 s14, s14, 28
	s_mul_i32 s15, s14, 0x2c00000
	s_waitcnt lgkmcnt(0)
	s_add_u32 s4, s4, s15
	s_addc_u32 s5, s5, 0
	s_mul_i32 s15, s14, 0x1600000
	s_add_u32 s15, s38, s15
	s_mulk_i32 s14, 0x1600
	s_addc_u32 s16, s39, 0
	s_sub_i32 s3, s3, s14
	s_lshl_b32 s14, s3, 5
	s_and_b32 s14, s14, 0x7e0
	s_and_b32 s3, s3, 0x1fc0
	s_lshl_b32 s17, s14, 2
	s_add_u32 s4, s4, s17
	v_or_b32_e32 v42, s3, v5
	s_addc_u32 s5, s5, 0
	v_lshl_add_u64 v[40:41], s[4:5], 0, v[2:3]
	v_lshlrev_b32_e32 v42, 13, v42
	v_mov_b32_e32 v43, v3
	v_lshl_add_u64 v[68:69], v[40:41], 0, v[42:43]
	v_add_co_u32_e32 v44, vcc, s34, v68
	s_lshl_b32 s3, s3, 1
	s_nop 0
	v_addc_co_u32_e32 v45, vcc, 0, v69, vcc
	v_add_co_u32_e32 v48, vcc, s35, v68
	global_load_dwordx4 v[40:43], v[68:69], off nt
	s_nop 0
	global_load_dwordx4 v[44:47], v[44:45], off nt
	v_addc_co_u32_e32 v49, vcc, 0, v69, vcc
	v_add_co_u32_e32 v52, vcc, s36, v68
	s_add_u32 s4, s15, s3
	s_nop 0
	v_addc_co_u32_e32 v53, vcc, 0, v69, vcc
	v_add_co_u32_e32 v56, vcc, s37, v68
	global_load_dwordx4 v[48:51], v[48:49], off nt
	s_nop 0
	global_load_dwordx4 v[52:55], v[52:53], off nt
	v_addc_co_u32_e32 v57, vcc, 0, v69, vcc
	v_add_co_u32_e32 v60, vcc, s40, v68
	v_lshlrev_b32_e32 v72, 1, v4
	s_nop 0
	v_addc_co_u32_e32 v61, vcc, 0, v69, vcc
	global_load_dwordx4 v[56:59], v[56:57], off nt
	s_nop 0
	global_load_dwordx4 v[60:63], v[60:61], off nt
	v_add_co_u32_e32 v64, vcc, s41, v68
	v_mov_b32_e32 v73, v3
	s_nop 0
	v_addc_co_u32_e32 v65, vcc, 0, v69, vcc
	global_load_dwordx4 v[64:67], v[64:65], off nt
	v_add_co_u32_e32 v68, vcc, s44, v68
	v_or_b32_e32 v74, s14, v5
	s_nop 0
	v_addc_co_u32_e32 v69, vcc, 0, v69, vcc
	global_load_dwordx4 v[68:71], v[68:69], off nt
	s_addc_u32 s5, s16, 0
	v_mov_b32_e32 v75, v3
	v_mul_u32_u24_e32 v74, 0x2c00, v74
	v_lshl_add_u64 v[72:73], s[4:5], 0, v[72:73]
	v_or_b32_e32 v76, s14, v20
	v_mul_u32_u24_e32 v76, 0x2c00, v76
	v_mov_b32_e32 v77, v3
	s_waitcnt vmcnt(7)
	ds_write2_b32 v23, v40, v41 offset1:1
	ds_write2_b32 v24, v42, v43 offset1:1
	s_waitcnt vmcnt(6)
	ds_write2_b32 v25, v44, v45 offset1:1
	ds_write2_b32 v26, v46, v47 offset1:1
	s_waitcnt vmcnt(5)
	ds_write2_b32 v27, v48, v49 offset1:1
	ds_write2_b32 v28, v50, v51 offset1:1
	s_waitcnt vmcnt(4)
	ds_write2_b32 v29, v52, v53 offset1:1
	ds_write2_b32 v30, v54, v55 offset1:1
	s_waitcnt vmcnt(3)
	ds_write2_b32 v31, v56, v57 offset1:1
	ds_write2_b32 v32, v58, v59 offset1:1
	s_waitcnt vmcnt(2)
	ds_write2_b32 v33, v60, v61 offset1:1
	ds_write2_b32 v34, v62, v63 offset1:1
	s_waitcnt vmcnt(1)
	ds_write2_b32 v35, v64, v65 offset1:1
	ds_write2_b32 v36, v66, v67 offset1:1
	s_waitcnt vmcnt(0)
	ds_write2_b32 v37, v68, v69 offset1:1
	ds_write2_b32 v38, v70, v71 offset1:1
	s_waitcnt lgkmcnt(0)
	ds_read2_b32 v[44:45], v39 offset0:33 offset1:41
	ds_read2_b32 v[46:47], v39 offset1:8
	ds_read2_b32 v[48:49], v39 offset0:66 offset1:74
	ds_read2_b32 v[50:51], v39 offset0:99 offset1:107
	ds_read2_b32 v[52:53], v39 offset0:132 offset1:140
	ds_read2_b32 v[54:55], v39 offset0:165 offset1:173
	ds_read2_b32 v[56:57], v39 offset0:198 offset1:206
	ds_read2_b32 v[58:59], v39 offset0:231 offset1:239
	v_lshl_add_u64 v[60:61], v[72:73], 0, v[74:75]
	s_waitcnt lgkmcnt(6)
	v_cvt_pk_bf16_f32 v40, v46, v44
	s_waitcnt lgkmcnt(4)
	v_cvt_pk_bf16_f32 v41, v48, v50
	s_waitcnt lgkmcnt(2)
	v_cvt_pk_bf16_f32 v42, v52, v54
	s_waitcnt lgkmcnt(0)
	v_cvt_pk_bf16_f32 v43, v56, v58
	global_store_dwordx4 v[60:61], v[40:43], off sc0 sc1
	v_cvt_pk_bf16_f32 v44, v47, v45
	v_cvt_pk_bf16_f32 v45, v49, v51
	v_cvt_pk_bf16_f32 v46, v53, v55
	v_cvt_pk_bf16_f32 v47, v57, v59
	ds_read2_b32 v[48:49], v39 offset0:16 offset1:24
	ds_read2_b32 v[50:51], v39 offset0:49 offset1:57
	ds_read2_b32 v[52:53], v39 offset0:82 offset1:90
	ds_read2_b32 v[54:55], v39 offset0:115 offset1:123
	ds_read2_b32 v[56:57], v39 offset0:148 offset1:156
	ds_read2_b32 v[58:59], v39 offset0:181 offset1:189
	ds_read2_b32 v[60:61], v39 offset0:214 offset1:222
	ds_read2_b32 v[62:63], v39 offset0:247 offset1:255
	v_lshl_add_u64 v[40:41], v[72:73], 0, v[76:77]
	global_store_dwordx4 v[40:41], v[44:47], off sc0 sc1
	s_waitcnt lgkmcnt(6)
	v_cvt_pk_bf16_f32 v40, v48, v50
	s_waitcnt lgkmcnt(4)
	v_cvt_pk_bf16_f32 v41, v52, v54
	v_or_b32_e32 v44, s14, v21
	v_mul_u32_u24_e32 v44, 0x2c00, v44
	v_mov_b32_e32 v45, v3
	s_waitcnt lgkmcnt(2)
	v_cvt_pk_bf16_f32 v42, v56, v58
	s_waitcnt lgkmcnt(0)
	v_cvt_pk_bf16_f32 v43, v60, v62
	v_lshl_add_u64 v[44:45], v[72:73], 0, v[44:45]
	global_store_dwordx4 v[44:45], v[40:43], off sc0 sc1
	v_or_b32_e32 v44, s14, v22
	v_mul_u32_u24_e32 v44, 0x2c00, v44
	v_mov_b32_e32 v45, v3
	v_cvt_pk_bf16_f32 v40, v49, v51
	v_cvt_pk_bf16_f32 v41, v53, v55
	v_cvt_pk_bf16_f32 v42, v57, v59
	v_cvt_pk_bf16_f32 v43, v61, v63
	v_lshl_add_u64 v[44:45], v[72:73], 0, v[44:45]
	global_store_dwordx4 v[44:45], v[40:43], off sc0 sc1
	s_waitcnt lgkmcnt(0)

.LBB0_68:
	s_andn2_b64 vcc, exec, s[4:5]
	s_cbranch_vccnz .LBB0_33
	s_mov_b64 s[4:5], s[70:71]
	s_load_dwordx2 s[4:5], s[4:5], 0x30
	s_mul_hi_i32 s3, s54, 0x2e8ba2e9
	s_lshr_b32 s14, s3, 31
	s_ashr_i32 s3, s3, 11
	s_add_i32 s3, s3, s14
	s_mul_i32 s15, s3, 0x5800000
	s_mul_hi_i32 s14, s3, 0x5800000
	s_waitcnt lgkmcnt(0)
	s_add_u32 s16, s4, s15
	s_addc_u32 s5, s5, s14
	s_mul_i32 s14, s3, 0x2c00000
	s_mul_hi_i32 s4, s3, 0x2c00000
	s_add_u32 s17, s42, s14
	s_mulk_i32 s3, 0xd400
	s_addc_u32 s18, s43, s4
	s_add_i32 s3, s54, s3
	s_mul_i32 s4, s3, 0xba3
	s_lshr_b32 s14, s4, 31
	s_ashr_i32 s4, s4, 20
	s_add_i32 s4, s4, s14
	s_mul_i32 s14, s4, 0x160
	s_sub_i32 s3, s3, s14
	s_sext_i32_i16 s3, s3
	s_lshl_b32 s14, s3, 5
	s_cmpk_gt_i32 s3, 0xaf
	s_cselect_b32 s3, 0xffffea00, 0
	s_cselect_b32 s15, 0x80, 0
	s_add_i32 s3, s3, s14
	s_lshl_b32 s3, s3, 1
	s_and_b32 s19, s14, 0x60
	s_and_b32 s3, s3, 0xffffff00
	s_or_b32 s15, s19, s15
	s_or_b32 s3, s15, s3
	s_ashr_i32 s15, s14, 31
	s_lshl_b32 s4, s4, 6
	s_lshl_b64 s[14:15], s[14:15], 2
	v_or_b32_e32 v42, s4, v5
	s_add_u32 s14, s16, s14
	s_addc_u32 s15, s5, s15
	v_mul_i32_i24_e32 v42, 0xb000, v42
	v_lshl_add_u64 v[40:41], s[14:15], 0, v[2:3]
	v_ashrrev_i32_e32 v43, 31, v42
	v_lshl_add_u64 v[68:69], v[40:41], 0, v[42:43]
	v_add_co_u32_e32 v44, vcc, s77, v68
	s_ashr_i32 s5, s4, 31
	s_nop 0
	v_addc_co_u32_e32 v45, vcc, 0, v69, vcc
	v_add_co_u32_e32 v48, vcc, s78, v68
	global_load_dwordx4 v[40:43], v[68:69], off nt
	s_nop 0
	global_load_dwordx4 v[44:47], v[44:45], off nt
	v_addc_co_u32_e32 v49, vcc, 0, v69, vcc
	v_add_co_u32_e32 v52, vcc, s79, v68
	s_lshl_b64 s[4:5], s[4:5], 1
	s_nop 0
	v_addc_co_u32_e32 v53, vcc, 0, v69, vcc
	v_add_co_u32_e32 v56, vcc, s80, v68
	global_load_dwordx4 v[48:51], v[48:49], off nt
	s_nop 0
	global_load_dwordx4 v[52:55], v[52:53], off nt
	v_addc_co_u32_e32 v57, vcc, 0, v69, vcc
	v_add_co_u32_e32 v60, vcc, s81, v68
	v_or_b32_e32 v74, s3, v5
	s_nop 0
	v_addc_co_u32_e32 v61, vcc, 0, v69, vcc
	global_load_dwordx4 v[56:59], v[56:57], off nt
	s_nop 0
	global_load_dwordx4 v[60:63], v[60:61], off nt
	v_add_co_u32_e32 v64, vcc, s82, v68
	s_add_u32 s4, s17, s4
	s_nop 0
	v_addc_co_u32_e32 v65, vcc, 0, v69, vcc
	global_load_dwordx4 v[64:67], v[64:65], off nt
	v_add_co_u32_e32 v68, vcc, s83, v68
	v_lshlrev_b32_e32 v72, 1, v4
	s_nop 0
	v_addc_co_u32_e32 v69, vcc, 0, v69, vcc
	global_load_dwordx4 v[68:71], v[68:69], off nt
	v_mov_b32_e32 v73, v3
	s_addc_u32 s5, s18, s5
	v_ashrrev_i32_e32 v75, 31, v74
	s_waitcnt vmcnt(7)
	ds_write2_b32 v23, v40, v41 offset1:1
	ds_write2_b32 v24, v42, v43 offset1:1
	s_waitcnt vmcnt(6)
	ds_write2_b32 v25, v44, v45 offset1:1
	ds_write2_b32 v26, v46, v47 offset1:1
	s_waitcnt vmcnt(5)
	ds_write2_b32 v27, v48, v49 offset1:1
	ds_write2_b32 v28, v50, v51 offset1:1
	s_waitcnt vmcnt(4)
	ds_write2_b32 v29, v52, v53 offset1:1
	ds_write2_b32 v30, v54, v55 offset1:1
	s_waitcnt vmcnt(3)
	ds_write2_b32 v31, v56, v57 offset1:1
	ds_write2_b32 v32, v58, v59 offset1:1
	s_waitcnt vmcnt(2)
	ds_write2_b32 v33, v60, v61 offset1:1
	ds_write2_b32 v34, v62, v63 offset1:1
	s_waitcnt vmcnt(1)
	ds_write2_b32 v35, v64, v65 offset1:1
	ds_write2_b32 v36, v66, v67 offset1:1
	s_waitcnt vmcnt(0)
	ds_write2_b32 v37, v68, v69 offset1:1
	ds_write2_b32 v38, v70, v71 offset1:1
	s_waitcnt lgkmcnt(0)
	ds_read2_b32 v[44:45], v39 offset0:33 offset1:41
	ds_read2_b32 v[46:47], v39 offset1:8
	ds_read2_b32 v[48:49], v39 offset0:66 offset1:74
	ds_read2_b32 v[50:51], v39 offset0:99 offset1:107
	ds_read2_b32 v[52:53], v39 offset0:132 offset1:140
	ds_read2_b32 v[54:55], v39 offset0:165 offset1:173
	ds_read2_b32 v[56:57], v39 offset0:198 offset1:206
	ds_read2_b32 v[58:59], v39 offset0:231 offset1:239
	v_lshl_add_u64 v[60:61], s[4:5], 0, v[72:73]
	v_lshlrev_b64 v[62:63], 12, v[74:75]
	s_waitcnt lgkmcnt(6)
	v_cvt_pk_bf16_f32 v40, v46, v44
	s_waitcnt lgkmcnt(4)
	v_cvt_pk_bf16_f32 v41, v48, v50
	s_waitcnt lgkmcnt(2)
	v_cvt_pk_bf16_f32 v42, v52, v54
	s_waitcnt lgkmcnt(0)
	v_cvt_pk_bf16_f32 v43, v56, v58
	v_lshl_add_u64 v[62:63], v[60:61], 0, v[62:63]
	v_or_b32_e32 v44, s3, v20
	global_store_dwordx4 v[62:63], v[40:43], off sc0 sc1
	s_nop 1
	v_cvt_pk_bf16_f32 v40, v47, v45
	v_ashrrev_i32_e32 v45, 31, v44
	v_cvt_pk_bf16_f32 v41, v49, v51
	v_cvt_pk_bf16_f32 v42, v53, v55
	v_cvt_pk_bf16_f32 v43, v57, v59
	v_lshlrev_b64 v[44:45], 12, v[44:45]
	ds_read2_b32 v[46:47], v39 offset0:49 offset1:57
	ds_read2_b32 v[48:49], v39 offset0:16 offset1:24
	ds_read2_b32 v[50:51], v39 offset0:82 offset1:90
	ds_read2_b32 v[52:53], v39 offset0:115 offset1:123
	ds_read2_b32 v[54:55], v39 offset0:148 offset1:156
	ds_read2_b32 v[56:57], v39 offset0:181 offset1:189
	ds_read2_b32 v[58:59], v39 offset0:214 offset1:222
	ds_read2_b32 v[62:63], v39 offset0:247 offset1:255
	v_lshl_add_u64 v[44:45], v[60:61], 0, v[44:45]
	global_store_dwordx4 v[44:45], v[40:43], off sc0 sc1
	v_or_b32_e32 v44, s3, v21
	v_ashrrev_i32_e32 v45, 31, v44
	v_lshlrev_b64 v[44:45], 12, v[44:45]
	s_waitcnt lgkmcnt(6)
	v_cvt_pk_bf16_f32 v40, v48, v46
	s_waitcnt lgkmcnt(4)
	v_cvt_pk_bf16_f32 v41, v50, v52
	s_waitcnt lgkmcnt(2)
	v_cvt_pk_bf16_f32 v42, v54, v56
	s_waitcnt lgkmcnt(0)
	v_cvt_pk_bf16_f32 v43, v58, v62
	v_lshl_add_u64 v[44:45], v[60:61], 0, v[44:45]
	global_store_dwordx4 v[44:45], v[40:43], off sc0 sc1
	v_or_b32_e32 v44, s3, v22
	v_ashrrev_i32_e32 v45, 31, v44
	v_lshlrev_b64 v[44:45], 12, v[44:45]
	v_cvt_pk_bf16_f32 v40, v49, v47
	v_cvt_pk_bf16_f32 v41, v51, v53
	v_cvt_pk_bf16_f32 v42, v55, v57
	v_cvt_pk_bf16_f32 v43, v59, v63
	v_lshl_add_u64 v[44:45], v[60:61], 0, v[44:45]
	global_store_dwordx4 v[44:45], v[40:43], off sc0 sc1
	s_waitcnt lgkmcnt(0)
	s_branch .LBB0_33

.LBB0_72:
	v_ashrrev_i32_e32 v9, 8, v8
	v_cmp_gt_i32_e32 vcc, s14, v9
	v_and_b32_e32 v4, 0x7f8, v3
	v_add_u32_e32 v8, s24, v8
	v_cndmask_b32_e32 v14, v6, v7, vcc
	v_add_u32_e32 v14, v14, v9
	v_ashrrev_i32_e32 v15, 31, v14
	v_lshlrev_b64 v[14:15], 12, v[14:15]
	v_lshlrev_b32_e32 v4, 1, v4
	v_cmp_lt_i32_e32 vcc, s15, v8
	v_lshl_add_u64 v[14:15], s[6:7], 0, v[14:15]
	v_add_u32_e32 v3, s3, v3
	s_or_b64 s[26:27], vcc, s[26:27]
	v_lshl_add_u64 v[14:15], v[14:15], 0, v[4:5]
	global_store_dwordx4 v[14:15], v[10:13], off sc0 sc1
	s_andn2_b64 exec, exec, s[26:27]
	s_cbranch_execnz .LBB0_72
